# retention scan: per-step LDS tiles double-buffered (odd steps use the second K'^T tile and a second V buffer), one workgroup barrier per scan step instead of two
# speedup vs baseline: 1.0105x; 1.0022x over previous
.LBB0_379:
	s_and_b64 vcc, exec, s[0:1]
	s_cbranch_vccz .LBB0_463
	v_bfe_u32 v100, v147, 2, 1
	v_and_b32_e32 v221, 1, v147
	v_mov_b32_e32 v219, 0
	v_mov_b32_e32 v223, 0
	s_nop 0
	v_mul_u32_u24_e32 v220, 0x4400, v221
	v_lshlrev_b32_e32 v218, 15, v221
	v_lshlrev_b32_e32 v222, 19, v221
	v_mul_u32_u24_e32 v221, 0x12000, v221
	s_add_i32 s0, 0, 0x24048
	s_add_i32 s1, 0, 0x24050
	v_mov_b32_e32 v0, s1
	v_mov_b32_e32 v1, s0
	v_cmp_eq_u32_e64 s[0:1], 0, v100
	v_bfe_u32 v2, v147, 3, 2
	v_mov_b32_e32 v137, 0
	v_cndmask_b32_e64 v0, v0, v1, s[0:1]
	ds_read_b64 v[0:1], v0
	v_lshlrev_b32_e32 v2, 2, v2
	v_mov_b32_e32 v3, v137
	s_add_i32 s12, 0, 0x240a8
	v_ashrrev_i32_e32 v5, 3, v147
	s_waitcnt lgkmcnt(0)
	v_lshl_add_u64 v[0:1], v[0:1], 0, v[2:3]
	global_load_dword v44, v[0:1], off
	v_and_b32_e32 v1, 4, v147
	v_lshrrev_b32_e32 v0, 3, v147
	v_cmp_ne_u32_e64 s[6:7], 0, v1
	v_mov_b32_e32 v1, s12
	v_bfi_b32 v96, -4, v5, v0
	ds_read_b64 v[0:1], v1
	v_mov_b32_e32 v2, 0x1ce00000
	v_mov_b32_e32 v3, 0x1cc00000
	v_lshlrev_b32_e32 v4, 6, v147
	v_and_b32_e32 v106, 0xc0, v4
	v_cndmask_b32_e64 v136, v2, v3, s[0:1]
	v_lshlrev_b32_e32 v2, 8, v96
	v_lshl_or_b32 v102, v96, 7, v135
	v_or3_b32 v104, v2, v106, v135
	v_ashrrev_i32_e32 v103, 31, v102
	v_ashrrev_i32_e32 v105, 31, v104
	v_lshlrev_b64 v[2:3], 9, v[102:103]
	v_lshlrev_b64 v[4:5], 9, v[104:105]
	s_waitcnt lgkmcnt(0)
	v_lshl_add_u64 v[6:7], v[0:1], 0, v[136:137]
	v_and_b32_e32 v134, 0x78, v158
	s_mov_b64 s[4:5], 0x1d000000
	v_lshlrev_b32_e32 v136, 8, v100
	v_lshl_add_u64 v[0:1], v[0:1], 0, v[4:5]
	v_lshl_add_u64 v[28:29], v[6:7], 0, v[2:3]
	v_lshlrev_b32_e32 v98, 1, v134
	v_mov_b32_e32 v99, v137
	v_lshl_add_u64 v[30:31], v[0:1], 0, s[4:5]
	v_lshl_add_u64 v[0:1], v[28:29], 0, v[136:137]
	s_movk_i32 s9, 0x2000
	v_lshl_add_u64 v[32:33], v[0:1], 0, v[98:99]
	v_lshl_add_u64 v[32:33], v[32:33], 0, v[218:219]
	v_add_co_u32_e32 v12, vcc, s9, v32
	s_movk_i32 s10, 0x4000
	s_nop 0
	v_addc_co_u32_e32 v13, vcc, 0, v33, vcc
	v_add_co_u32_e32 v14, vcc, s10, v32
	s_movk_i32 s11, 0x6000
	s_nop 0
	v_addc_co_u32_e32 v15, vcc, 0, v33, vcc
	v_add_co_u32_e32 v34, vcc, s11, v32
	s_mov_b32 s13, 0x8000
	s_nop 0
	v_addc_co_u32_e32 v35, vcc, 0, v33, vcc
	v_add_co_u32_e32 v36, vcc, s13, v32
	s_mov_b32 s14, 0xa000
	s_nop 0
	v_addc_co_u32_e32 v37, vcc, 0, v33, vcc
	v_add_co_u32_e32 v38, vcc, s14, v32
	s_mov_b32 s15, 0xc000
	s_nop 0
	v_addc_co_u32_e32 v39, vcc, 0, v33, vcc
	v_add_co_u32_e32 v42, vcc, s15, v32
	s_mov_b32 s16, 0xe000
	v_lshl_add_u64 v[2:3], v[30:31], 0, v[136:137]
	v_addc_co_u32_e32 v43, vcc, 0, v33, vcc
	v_lshl_add_u64 v[40:41], v[2:3], 0, v[98:99]
	global_load_dwordx4 v[0:3], v[12:13], off
	global_load_dwordx4 v[4:7], v[14:15], off
	global_load_dwordx4 v[8:11], v[34:35], off
	v_add_co_u32_e32 v42, vcc, s16, v32
	s_mov_b32 s8, 0x3fb8aa3b
	s_nop 0
	v_addc_co_u32_e32 v43, vcc, 0, v33, vcc
	v_add_co_u32_e32 v48, vcc, s9, v40
	v_xor_b32_e32 v136, 0x100, v136
	s_nop 0
	v_addc_co_u32_e32 v49, vcc, 0, v41, vcc
	v_lshl_add_u64 v[28:29], v[28:29], 0, v[136:137]
	v_lshl_add_u64 v[76:77], v[28:29], 0, v[98:99]
	v_lshl_add_u64 v[76:77], v[76:77], 0, v[218:219]
	v_lshl_add_u64 v[28:29], v[30:31], 0, v[136:137]
	v_lshl_add_u64 v[88:89], v[28:29], 0, v[98:99]
	v_mov_b32_e32 v97, 0x12800000
	s_mov_b32 s4, 0xc2ce8ed0
	s_waitcnt vmcnt(0)
	v_mul_f32_e32 v107, 0x43000000, v44
	v_mul_f32_e32 v108, 0x3fb8aa3b, v107
	v_fma_f32 v12, v107, s8, -v108
	v_fmamk_f32 v110, v107, 0x32a5705f, v12
	global_load_dwordx4 v[12:15], v[32:33], off
	global_load_dwordx4 v[36:39], v[40:41], off
	s_nop 0
	global_load_dwordx4 v[44:47], v[48:49], off
	v_add_co_u32_e32 v42, vcc, s10, v40
	v_rndne_f32_e32 v109, v108
	s_nop 0
	v_addc_co_u32_e32 v43, vcc, 0, v41, vcc
	v_add_co_u32_e32 v40, vcc, s11, v40
	v_sub_f32_e32 v99, v108, v109
	s_nop 0
	v_addc_co_u32_e32 v41, vcc, 0, v41, vcc
	v_add_co_u32_e32 v48, vcc, s9, v76
	global_load_dwordx4 v[60:63], v[42:43], off
	global_load_dwordx4 v[64:67], v[40:41], off
	v_addc_co_u32_e32 v49, vcc, 0, v77, vcc
	v_add_co_u32_e32 v50, vcc, s10, v76
	v_add_f32_e32 v99, v99, v110
	s_nop 0
	v_addc_co_u32_e32 v51, vcc, 0, v77, vcc
	v_add_co_u32_e32 v52, vcc, s11, v76
	global_load_dwordx4 v[28:31], v[48:49], off
	global_load_dwordx4 v[40:43], v[50:51], off
	v_addc_co_u32_e32 v53, vcc, 0, v77, vcc
	v_add_co_u32_e32 v54, vcc, s13, v76
	v_exp_f32_e32 v99, v99
	s_nop 0
	v_addc_co_u32_e32 v55, vcc, 0, v77, vcc
	global_load_dwordx4 v[48:51], v[52:53], off
	v_add_co_u32_e32 v52, vcc, s14, v76
	v_cvt_i32_f32_e32 v108, v109
	s_nop 0
	v_addc_co_u32_e32 v53, vcc, 0, v77, vcc
	v_add_co_u32_e32 v54, vcc, s15, v76
	v_mov_b32_e32 v109, 0x10800000
	s_nop 0
	v_addc_co_u32_e32 v55, vcc, 0, v77, vcc
	v_add_co_u32_e32 v90, vcc, s16, v76
	v_addc_co_u32_e32 v91, vcc, 0, v77, vcc
	v_add_co_u32_e32 v92, vcc, s9, v88
	global_load_dwordx4 v[52:55], v[76:77], off
	global_load_dwordx4 v[80:83], v[88:89], off
	v_addc_co_u32_e32 v93, vcc, 0, v89, vcc
	global_load_dwordx4 v[84:87], v[92:93], off
	v_add_co_u32_e32 v90, vcc, s10, v88
	v_cndmask_b32_e64 v138, v97, v109, s[0:1]
	s_nop 0
	v_addc_co_u32_e32 v91, vcc, 0, v89, vcc
	v_add_co_u32_e32 v92, vcc, s11, v88
	v_ldexp_f32 v97, v99, v108
	s_nop 0
	v_addc_co_u32_e32 v93, vcc, 0, v89, vcc
	global_load_dwordx4 v[88:91], v[90:91], off
	s_nop 0
	global_load_dwordx4 v[92:95], v[92:93], off
	v_cmp_ngt_f32_e32 vcc, s4, v107
	s_mov_b32 s4, 0x42b17218
	v_mov_b32_e32 v99, 0x7f800000
	v_cndmask_b32_e32 v97, 0, v97, vcc
	v_cmp_nlt_f32_e32 vcc, s4, v107
	v_and_b32_e32 v165, 48, v101
	v_or_b32_e32 v163, v165, v129
	v_cndmask_b32_e32 v140, v99, v97, vcc
	v_mul_u32_u24_e32 v97, 0x88, v135
	v_lshlrev_b32_e32 v97, 1, v97
	v_add3_u32 v159, v161, v97, v98
	v_or_b32_e32 v98, v106, v163
	s_movk_i32 s4, 0x110
	v_mul_u32_u24_e32 v164, 0x88, v129
	v_ashrrev_i32_e32 v97, 31, v96
	v_lshlrev_b32_e32 v98, 7, v98
	s_mov_b32 s3, 0
	v_mov_b32_e32 v139, v137
	v_mov_b32_e32 v141, v140
	v_mov_b32_e32 v142, v140
	v_mov_b32_e32 v143, v140
	v_mad_u32_u24 v166, v163, s4, v155
	v_lshl_add_u32 v167, v164, 1, v155
	v_sub_u32_e32 v216, v159, v221
	v_sub_u32_e32 v217, v167, v221
	v_add_u32_e32 v216, v216, v220
	v_add_u32_e32 v224, 0x12000, v216
	v_add_u32_e32 v225, 0x12000, v217
	v_lshlrev_b64 v[144:145], 13, v[102:103]
	v_lshlrev_b64 v[146:147], 13, v[104:105]
	v_lshlrev_b64 v[148:149], 22, v[96:97]
	v_lshlrev_b32_e32 v150, 16, v100
	v_mov_b32_e32 v151, v137
	s_mov_b32 s13, 30
	s_add_i32 s14, 0, 0x240a0
	v_lshlrev_b32_e32 v152, 1, v98
	s_mov_b32 s15, 0x20000
	s_mov_b32 s16, 0x40000
	s_mov_b32 s17, 0x60000
	s_mov_b32 s18, 0x80000
	s_mov_b32 s19, 0xa0000
	s_mov_b32 s20, 0xc0000
	s_mov_b32 s21, 0xe0000
	s_mov_b32 s22, 0x14800000
	s_mov_b32 s23, 0
	v_mov_b32_e32 v124, v137
	v_mov_b32_e32 v125, v137
	v_mov_b32_e32 v126, v137
	v_mov_b32_e32 v127, v137
	v_mov_b32_e32 v120, v137
	v_mov_b32_e32 v121, v137
	v_mov_b32_e32 v122, v137
	v_mov_b32_e32 v123, v137
	v_mov_b32_e32 v112, v137
	v_mov_b32_e32 v113, v137
	v_mov_b32_e32 v114, v137
	v_mov_b32_e32 v115, v137
	v_mov_b32_e32 v108, v137
	v_mov_b32_e32 v109, v137
	v_mov_b32_e32 v110, v137
	v_mov_b32_e32 v111, v137
	v_mov_b32_e32 v104, v137
	v_mov_b32_e32 v105, v137
	v_mov_b32_e32 v106, v137
	v_mov_b32_e32 v107, v137
	v_mov_b32_e32 v100, v137
	v_mov_b32_e32 v101, v137
	v_mov_b32_e32 v102, v137
	v_mov_b32_e32 v103, v137
	v_mov_b32_e32 v96, v137
	v_mov_b32_e32 v97, v137
	v_mov_b32_e32 v98, v137
	v_mov_b32_e32 v99, v137
	v_mov_b32_e32 v116, v137
	v_mov_b32_e32 v117, v137
	v_mov_b32_e32 v118, v137
	v_mov_b32_e32 v119, v137
	s_branch .LBB0_382
.LBB0_381:
	s_waitcnt lgkmcnt(0)
	s_barrier
	ds_read_b128 v[240:243], v166 offset:52224
	ds_read_b128 v[244:247], v166 offset:52288
	ds_read_b128 v[248:251], v166 offset:52352
	ds_read_b128 v[252:255], v166 offset:52416
	ds_read_b128 v[168:171], v225
	ds_read_b128 v[172:175], v225 offset:4352
	ds_read_b128 v[176:179], v225 offset:8704
	ds_read_b128 v[180:183], v225 offset:13056
	ds_read_b128 v[184:187], v225 offset:17408
	ds_read_b128 v[188:191], v225 offset:21760
	ds_read_b128 v[192:195], v225 offset:26112
	ds_read_b128 v[196:199], v225 offset:30464
	ds_read_b128 v[200:203], v225 offset:64
	ds_read_b128 v[204:207], v225 offset:4416
	ds_read_b128 v[208:211], v225 offset:8768
	v_pk_mul_f32 v[126:127], v[142:143], v[126:127]
	v_pk_mul_f32 v[124:125], v[140:141], v[124:125]
	v_pk_mul_f32 v[122:123], v[142:143], v[122:123]
	v_pk_mul_f32 v[120:121], v[140:141], v[120:121]
	v_pk_mul_f32 v[118:119], v[142:143], v[118:119]
	v_pk_mul_f32 v[116:117], v[140:141], v[116:117]
	v_pk_mul_f32 v[114:115], v[142:143], v[114:115]
	v_pk_mul_f32 v[112:113], v[140:141], v[112:113]
	v_pk_mul_f32 v[110:111], v[142:143], v[110:111]
	v_pk_mul_f32 v[108:109], v[140:141], v[108:109]
	v_pk_mul_f32 v[106:107], v[142:143], v[106:107]
	v_pk_mul_f32 v[104:105], v[140:141], v[104:105]
	v_pk_mul_f32 v[102:103], v[142:143], v[102:103]
	v_pk_mul_f32 v[100:101], v[140:141], v[100:101]
	v_pk_mul_f32 v[98:99], v[142:143], v[98:99]
	v_pk_mul_f32 v[96:97], v[140:141], v[96:97]
	s_waitcnt lgkmcnt(10)
	v_mfma_f32_16x16x32_bf16 v[124:127], v[168:171], v[240:243], v[124:127]
	ds_read_b128 v[168:171], v225 offset:13120
	s_waitcnt lgkmcnt(10)
	v_mfma_f32_16x16x32_bf16 v[120:123], v[172:175], v[240:243], v[120:123]
	ds_read_b128 v[172:175], v225 offset:17472
	s_waitcnt lgkmcnt(10)
	v_mfma_f32_16x16x32_bf16 v[116:119], v[176:179], v[240:243], v[116:119]
	ds_read_b128 v[176:179], v225 offset:21824
	s_waitcnt lgkmcnt(10)
	v_mfma_f32_16x16x32_bf16 v[112:115], v[180:183], v[240:243], v[112:115]
	ds_read_b128 v[180:183], v225 offset:26176
	s_waitcnt lgkmcnt(10)
	v_mfma_f32_16x16x32_bf16 v[108:111], v[184:187], v[240:243], v[108:111]
	ds_read_b128 v[184:187], v225 offset:30528
	s_waitcnt lgkmcnt(10)
	v_mfma_f32_16x16x32_bf16 v[104:107], v[188:191], v[240:243], v[104:107]
	ds_read_b128 v[188:191], v225 offset:128
	s_waitcnt lgkmcnt(10)
	v_mfma_f32_16x16x32_bf16 v[100:103], v[192:195], v[240:243], v[100:103]
	ds_read_b128 v[192:195], v225 offset:4480
	s_waitcnt lgkmcnt(10)
	v_mfma_f32_16x16x32_bf16 v[96:99], v[196:199], v[240:243], v[96:99]
	ds_read_b128 v[196:199], v225 offset:8832
	s_waitcnt lgkmcnt(10)
	v_mfma_f32_16x16x32_bf16 v[124:127], v[200:203], v[244:247], v[124:127]
	ds_read_b128 v[200:203], v225 offset:13184
	s_waitcnt lgkmcnt(10)
	v_mfma_f32_16x16x32_bf16 v[120:123], v[204:207], v[244:247], v[120:123]
	ds_read_b128 v[204:207], v225 offset:17536
	s_waitcnt lgkmcnt(10)
	v_mfma_f32_16x16x32_bf16 v[116:119], v[208:211], v[244:247], v[116:119]
	ds_read_b128 v[208:211], v225 offset:21888
	s_waitcnt lgkmcnt(10)
	v_mfma_f32_16x16x32_bf16 v[112:115], v[168:171], v[244:247], v[112:115]
	ds_read_b128 v[168:171], v225 offset:26240
	s_waitcnt lgkmcnt(10)
	v_mfma_f32_16x16x32_bf16 v[108:111], v[172:175], v[244:247], v[108:111]
	ds_read_b128 v[172:175], v225 offset:30592
	s_waitcnt lgkmcnt(10)
	v_mfma_f32_16x16x32_bf16 v[104:107], v[176:179], v[244:247], v[104:107]
	ds_read_b128 v[176:179], v225 offset:192
	s_waitcnt lgkmcnt(10)
	v_mfma_f32_16x16x32_bf16 v[100:103], v[180:183], v[244:247], v[100:103]
	ds_read_b128 v[180:183], v225 offset:4544
	s_waitcnt lgkmcnt(10)
	v_mfma_f32_16x16x32_bf16 v[96:99], v[184:187], v[244:247], v[96:99]
	ds_read_b128 v[184:187], v225 offset:26304
	s_waitcnt lgkmcnt(10)
	v_mfma_f32_16x16x32_bf16 v[124:127], v[188:191], v[248:251], v[124:127]
	ds_read_b128 v[188:191], v225 offset:21952
	s_waitcnt lgkmcnt(10)
	v_mfma_f32_16x16x32_bf16 v[120:123], v[192:195], v[248:251], v[120:123]
	ds_read_b128 v[192:195], v225 offset:17600
	s_waitcnt lgkmcnt(10)
	v_mfma_f32_16x16x32_bf16 v[116:119], v[196:199], v[248:251], v[116:119]
	ds_read_b128 v[196:199], v225 offset:13248
	s_waitcnt lgkmcnt(10)
	v_mfma_f32_16x16x32_bf16 v[112:115], v[200:203], v[248:251], v[112:115]
	ds_read_b128 v[200:203], v225 offset:8896
	s_waitcnt lgkmcnt(10)
	v_mfma_f32_16x16x32_bf16 v[108:111], v[204:207], v[248:251], v[108:111]
	ds_read_b128 v[204:207], v225 offset:30656
	s_waitcnt lgkmcnt(10)
	v_mfma_f32_16x16x32_bf16 v[104:107], v[208:211], v[248:251], v[104:107]
	s_waitcnt lgkmcnt(9)
	v_mfma_f32_16x16x32_bf16 v[100:103], v[168:171], v[248:251], v[100:103]
	s_waitcnt lgkmcnt(8)
	v_mfma_f32_16x16x32_bf16 v[212:215], v[172:175], v[248:251], v[96:99]
	s_waitcnt lgkmcnt(7)
	v_mfma_f32_16x16x32_bf16 v[124:127], v[176:179], v[252:255], v[124:127]
	s_waitcnt lgkmcnt(6)
	v_mfma_f32_16x16x32_bf16 v[120:123], v[180:183], v[252:255], v[120:123]
	s_waitcnt lgkmcnt(5)
	v_mfma_f32_16x16x32_bf16 v[96:99], v[184:187], v[252:255], v[100:103]
	s_waitcnt lgkmcnt(4)
	v_mfma_f32_16x16x32_bf16 v[100:103], v[188:191], v[252:255], v[104:107]
	s_waitcnt lgkmcnt(3)
	v_mfma_f32_16x16x32_bf16 v[104:107], v[192:195], v[252:255], v[108:111]
	s_waitcnt lgkmcnt(2)
	v_mfma_f32_16x16x32_bf16 v[108:111], v[196:199], v[252:255], v[112:115]
	s_waitcnt lgkmcnt(1)
	v_mfma_f32_16x16x32_bf16 v[112:115], v[200:203], v[252:255], v[116:119]
	s_waitcnt lgkmcnt(0)
	v_mfma_f32_16x16x32_bf16 v[116:119], v[204:207], v[252:255], v[212:215]
	s_add_i32 s23, s23, 1
	s_add_i32 s3, s3, 2
	s_add_i32 s13, s13, -2
	s_cmp_lg_u32 s3, 34
	s_cbranch_scc0 .LBB0_406
.LBB0_382:
	s_lshl_b32 s24, s23, 1
	s_cmp_lg_u32 s3, 0
	s_cselect_b64 s[8:9], -1, 0
	s_and_b64 vcc, exec, s[8:9]
	s_waitcnt lgkmcnt(0)
	s_waitcnt vmcnt(8)
	s_cbranch_vccz .LBB0_404
	s_and_saveexec_b64 s[4:5], s[6:7]
	s_xor_b64 s[4:5], exec, s[4:5]
	s_sub_i32 s10, 33, s24
	s_or_saveexec_b64 s[4:5], s[4:5]
	v_mov_b32_e32 v136, s10
	s_xor_b64 exec, exec, s[4:5]
	s_add_i32 s10, s3, -2
	v_mov_b32_e32 v136, s10
	s_or_b64 exec, exec, s[4:5]
	s_cbranch_execnz .LBB0_389

.LBB0_393:
	s_waitcnt lgkmcnt(0)
	s_barrier
	ds_read_b128 v[240:243], v166 offset:34816
	ds_read_b128 v[244:247], v166 offset:34880
	ds_read_b128 v[248:251], v166 offset:34944
	ds_read_b128 v[252:255], v166 offset:35008
	ds_read_b128 v[168:171], v217
	ds_read_b128 v[172:175], v217 offset:4352
	ds_read_b128 v[176:179], v217 offset:8704
	ds_read_b128 v[180:183], v217 offset:13056
	ds_read_b128 v[184:187], v217 offset:17408
	ds_read_b128 v[188:191], v217 offset:21760
	ds_read_b128 v[192:195], v217 offset:26112
	ds_read_b128 v[196:199], v217 offset:30464
	ds_read_b128 v[200:203], v217 offset:64
	ds_read_b128 v[204:207], v217 offset:4416
	ds_read_b128 v[208:211], v217 offset:8768
	v_pk_mul_f32 v[126:127], v[142:143], v[126:127]
	v_pk_mul_f32 v[124:125], v[140:141], v[124:125]
	v_pk_mul_f32 v[122:123], v[142:143], v[122:123]
	v_pk_mul_f32 v[120:121], v[140:141], v[120:121]
	v_pk_mul_f32 v[114:115], v[142:143], v[114:115]
	v_pk_mul_f32 v[112:113], v[140:141], v[112:113]
	v_pk_mul_f32 v[110:111], v[142:143], v[110:111]
	v_pk_mul_f32 v[108:109], v[140:141], v[108:109]
	v_pk_mul_f32 v[106:107], v[142:143], v[106:107]
	v_pk_mul_f32 v[104:105], v[140:141], v[104:105]
	v_pk_mul_f32 v[102:103], v[142:143], v[102:103]
	v_pk_mul_f32 v[100:101], v[140:141], v[100:101]
	v_pk_mul_f32 v[98:99], v[142:143], v[98:99]
	v_pk_mul_f32 v[96:97], v[140:141], v[96:97]
	v_pk_mul_f32 v[118:119], v[142:143], v[118:119]
	v_pk_mul_f32 v[116:117], v[140:141], v[116:117]
	s_waitcnt lgkmcnt(10)
	v_mfma_f32_16x16x32_bf16 v[124:127], v[168:171], v[240:243], v[124:127]
	ds_read_b128 v[168:171], v217 offset:13120
	s_waitcnt lgkmcnt(10)
	v_mfma_f32_16x16x32_bf16 v[120:123], v[172:175], v[240:243], v[120:123]
	ds_read_b128 v[172:175], v217 offset:17472
	s_waitcnt lgkmcnt(10)
	v_mfma_f32_16x16x32_bf16 v[112:115], v[176:179], v[240:243], v[112:115]
	ds_read_b128 v[176:179], v217 offset:21824
	s_waitcnt lgkmcnt(10)
	v_mfma_f32_16x16x32_bf16 v[108:111], v[180:183], v[240:243], v[108:111]
	ds_read_b128 v[180:183], v217 offset:26176
	s_waitcnt lgkmcnt(10)
	v_mfma_f32_16x16x32_bf16 v[104:107], v[184:187], v[240:243], v[104:107]
	ds_read_b128 v[184:187], v217 offset:30528
	s_waitcnt lgkmcnt(10)
	v_mfma_f32_16x16x32_bf16 v[100:103], v[188:191], v[240:243], v[100:103]
	ds_read_b128 v[188:191], v217 offset:128
	s_waitcnt lgkmcnt(10)
	v_mfma_f32_16x16x32_bf16 v[96:99], v[192:195], v[240:243], v[96:99]
	ds_read_b128 v[192:195], v217 offset:4480
	s_waitcnt lgkmcnt(10)
	v_mfma_f32_16x16x32_bf16 v[116:119], v[196:199], v[240:243], v[116:119]
	ds_read_b128 v[196:199], v217 offset:8832
	s_waitcnt lgkmcnt(10)
	v_mfma_f32_16x16x32_bf16 v[124:127], v[200:203], v[244:247], v[124:127]
	ds_read_b128 v[200:203], v217 offset:13184
	s_waitcnt lgkmcnt(10)
	v_mfma_f32_16x16x32_bf16 v[120:123], v[204:207], v[244:247], v[120:123]
	ds_read_b128 v[204:207], v217 offset:17536
	s_waitcnt lgkmcnt(10)
	v_mfma_f32_16x16x32_bf16 v[112:115], v[208:211], v[244:247], v[112:115]
	ds_read_b128 v[208:211], v217 offset:21888
	s_waitcnt lgkmcnt(10)
	v_mfma_f32_16x16x32_bf16 v[108:111], v[168:171], v[244:247], v[108:111]
	ds_read_b128 v[168:171], v217 offset:26240
	s_waitcnt lgkmcnt(10)
	v_mfma_f32_16x16x32_bf16 v[104:107], v[172:175], v[244:247], v[104:107]
	ds_read_b128 v[172:175], v217 offset:30592
	s_waitcnt lgkmcnt(10)
	v_mfma_f32_16x16x32_bf16 v[100:103], v[176:179], v[244:247], v[100:103]
	ds_read_b128 v[176:179], v217 offset:192
	s_waitcnt lgkmcnt(10)
	v_mfma_f32_16x16x32_bf16 v[96:99], v[180:183], v[244:247], v[96:99]
	ds_read_b128 v[180:183], v217 offset:4544
	s_waitcnt lgkmcnt(10)
	v_mfma_f32_16x16x32_bf16 v[116:119], v[184:187], v[244:247], v[116:119]
	ds_read_b128 v[184:187], v217 offset:8896
	s_waitcnt lgkmcnt(10)
	v_mfma_f32_16x16x32_bf16 v[124:127], v[188:191], v[248:251], v[124:127]
	ds_read_b128 v[188:191], v217 offset:13248
	s_waitcnt lgkmcnt(10)
	v_mfma_f32_16x16x32_bf16 v[120:123], v[192:195], v[248:251], v[120:123]
	ds_read_b128 v[192:195], v217 offset:17600
	s_waitcnt lgkmcnt(10)
	v_mfma_f32_16x16x32_bf16 v[112:115], v[196:199], v[248:251], v[112:115]
	ds_read_b128 v[196:199], v217 offset:21952
	s_waitcnt lgkmcnt(10)
	v_mfma_f32_16x16x32_bf16 v[108:111], v[200:203], v[248:251], v[108:111]
	ds_read_b128 v[200:203], v217 offset:26304
	s_waitcnt lgkmcnt(10)
	v_mfma_f32_16x16x32_bf16 v[104:107], v[204:207], v[248:251], v[104:107]
	ds_read_b128 v[204:207], v217 offset:30656
	s_waitcnt lgkmcnt(10)
	v_mfma_f32_16x16x32_bf16 v[100:103], v[208:211], v[248:251], v[100:103]
	s_waitcnt lgkmcnt(9)
	v_mfma_f32_16x16x32_bf16 v[96:99], v[168:171], v[248:251], v[96:99]
	s_waitcnt lgkmcnt(8)
	v_mfma_f32_16x16x32_bf16 v[212:215], v[172:175], v[248:251], v[116:119]
	s_waitcnt lgkmcnt(0)
	s_waitcnt vmcnt(4)
	v_mfma_f32_16x16x32_bf16 v[124:127], v[176:179], v[252:255], v[124:127]
	v_mfma_f32_16x16x32_bf16 v[120:123], v[180:183], v[252:255], v[120:123]
	v_mfma_f32_16x16x32_bf16 v[116:119], v[184:187], v[252:255], v[112:115]
	v_mfma_f32_16x16x32_bf16 v[112:115], v[188:191], v[252:255], v[108:111]
	v_mfma_f32_16x16x32_bf16 v[108:111], v[192:195], v[252:255], v[104:107]
	v_mfma_f32_16x16x32_bf16 v[104:107], v[196:199], v[252:255], v[100:103]
	v_mfma_f32_16x16x32_bf16 v[100:103], v[200:203], v[252:255], v[96:99]
	v_mfma_f32_16x16x32_bf16 v[96:99], v[204:207], v[252:255], v[212:215]
	s_and_b64 vcc, exec, s[8:9]
	s_cbranch_vccz .LBB0_405
	s_and_saveexec_b64 s[8:9], s[6:7]
	s_xor_b64 s[8:9], exec, s[8:9]
	s_or_b32 s24, s24, 1
	s_sub_i32 s25, 33, s24
	s_or_saveexec_b64 s[8:9], s[8:9]
	v_mov_b32_e32 v136, s25
	s_xor_b64 exec, exec, s[8:9]
	s_add_i32 s24, s3, -1
	v_mov_b32_e32 v136, s24
	s_or_b64 exec, exec, s[8:9]
	s_add_i32 s8, s3, 1
	s_cbranch_execnz .LBB0_400

.LBB0_402:
	s_andn2_b64 vcc, exec, s[10:11]
	ds_write_b128 v224, v[52:55]
	ds_write_b128 v224, v[28:31] offset:4352
	ds_write_b128 v224, v[40:43] offset:8704
	ds_write_b128 v224, v[48:51] offset:13056
	ds_write_b128 v159, v[80:83] offset:52224
	ds_write_b128 v159, v[84:87] offset:56576
	ds_write_b128 v159, v[88:91] offset:60928
	ds_write_b128 v159, v[92:95] offset:65280
	s_cbranch_vccnz .LBB0_381
	v_mov_b32_e32 v28, s12
	ds_read_b64 v[28:29], v28
	v_mov_b32_e32 v30, s13
	v_mov_b32_e32 v31, s8
	v_cndmask_b32_e64 v30, v30, v31, s[0:1]
	v_lshlrev_b32_e32 v136, 8, v30
	s_waitcnt lgkmcnt(0)
	v_lshl_add_u64 v[30:31], v[28:29], 0, v[138:139]
	v_lshl_add_u64 v[30:31], v[30:31], 0, v[144:145]
	v_lshl_add_u64 v[30:31], v[30:31], 0, v[136:137]
	v_lshlrev_b32_e32 v40, 1, v134
	v_mov_b32_e32 v41, v137
	v_lshl_add_u64 v[28:29], v[28:29], 0, v[146:147]
	v_lshl_add_u64 v[72:73], v[30:31], 0, v[40:41]
	v_lshl_add_u64 v[72:73], v[72:73], 0, v[222:223]
	v_lshl_add_u64 v[28:29], v[28:29], 0, v[136:137]
	v_lshl_add_u64 v[88:89], v[28:29], 0, v[40:41]
	v_add_co_u32_e32 v28, vcc, s15, v72
	s_nop 1
	v_addc_co_u32_e32 v29, vcc, 0, v73, vcc
	v_add_co_u32_e32 v40, vcc, s16, v72
	global_load_dwordx4 v[52:55], v[72:73], off
	s_nop 0
	global_load_dwordx4 v[28:31], v[28:29], off
	v_addc_co_u32_e32 v41, vcc, 0, v73, vcc
	v_add_co_u32_e32 v48, vcc, s17, v72
	s_nop 1
	v_addc_co_u32_e32 v49, vcc, 0, v73, vcc
	v_add_co_u32_e32 v56, vcc, s18, v72
	global_load_dwordx4 v[40:43], v[40:41], off
	s_nop 0
	global_load_dwordx4 v[48:51], v[48:49], off
	v_addc_co_u32_e32 v57, vcc, 0, v73, vcc
	v_add_co_u32_e32 v68, vcc, s19, v72
	s_nop 1
	v_addc_co_u32_e32 v69, vcc, 0, v73, vcc
	v_add_co_u32_e32 v74, vcc, s20, v72
	s_nop 0
	v_addc_co_u32_e32 v75, vcc, 0, v73, vcc
	v_add_co_u32_e32 v76, vcc, s21, v72
	s_nop 1
	v_addc_co_u32_e32 v77, vcc, 0, v73, vcc
	v_add_co_u32_e32 v80, vcc, s22, v88
	s_nop 0
	v_addc_co_u32_e32 v81, vcc, 0, v89, vcc
	v_add_co_u32_e32 v84, vcc, 0x14820000, v88
	s_nop 1
	v_addc_co_u32_e32 v85, vcc, 0, v89, vcc
	v_add_co_u32_e32 v90, vcc, 0x14840000, v88
	global_load_dwordx4 v[80:83], v[80:81], off
	s_nop 0
	global_load_dwordx4 v[84:87], v[84:85], off
	v_addc_co_u32_e32 v91, vcc, 0, v89, vcc
	v_add_co_u32_e32 v92, vcc, 0x14860000, v88
	s_nop 1
	v_addc_co_u32_e32 v93, vcc, 0, v89, vcc
	global_load_dwordx4 v[88:91], v[90:91], off
	s_nop 0
	global_load_dwordx4 v[92:95], v[92:93], off
	s_branch .LBB0_381
